# v23 + all grid-barrier protocol loads/atomics issued as global_ instead of flat_ (220 instructions)
# baseline (speedup 1.0000x reference)
; __device__ __forceinline__ unsigned xb_ld(unsigned* p)              { return __hip_atomic_load(p, __ATOMIC_RELAXED, __HIP_MEMORY_SCOPE_AGENT); }
; __device__ __forceinline__ void xcd_barrier_complete(unsigned* bar, unsigned x, unsigned& nloc, unsigned& nx) {
;     const unsigned G = gridDim.x * gridDim.y * gridDim.z;
;     unsigned sum, cnt, mine, sp = 0u;
;     for (;;) {
;         sum = 0u; cnt = 0u; mine = 0u;
; #pragma unroll
;         for (unsigned j = 0; j < 16; ++j) { const unsigned c = xb_ld(&bar[XB_XCNT(j)]); sum += c; cnt += (c > 0u) ? 1u : 0u; mine = (j == x) ? c : mine; }
;         if (sum == G) break;
;         __builtin_amdgcn_s_sleep(1);
;         if ((++sp & 255u) == 0u) { if (xb_ld(&bar[XB_TMO])) break; if (sp > XB_SPIN_CAP) { atomicAdd(&bar[XB_TMO], 1u); break; } }
;     }
;     nloc = mine > 0u ? mine : 1u; nx = cnt > 0u ? cnt : 1u;
; }
.LBB0_89:
	global_load_dword v25, v[0:1], off offset:1024 sc1
	global_load_dword v10, v[0:1], off offset:1280 sc1
	global_load_dword v11, v[0:1], off offset:1536 sc1
	global_load_dword v12, v[0:1], off offset:1792 sc1
	global_load_dword v13, v[0:1], off offset:2048 sc1
	global_load_dword v14, v[0:1], off offset:2304 sc1
	global_load_dword v15, v[0:1], off offset:2560 sc1
	global_load_dword v16, v[0:1], off offset:2816 sc1
	global_load_dword v17, v[0:1], off offset:3072 sc1
	global_load_dword v18, v[0:1], off offset:3328 sc1
	global_load_dword v19, v[0:1], off offset:3584 sc1
	global_load_dword v20, v[0:1], off offset:3840 sc1
	global_load_dword v21, v[2:3], off sc1
	global_load_dword v22, v[4:5], off sc1
	global_load_dword v23, v[6:7], off sc1
	global_load_dword v24, v[8:9], off sc1
	s_or_b64 s[6:7], s[6:7], exec
	s_or_b64 s[4:5], s[4:5], exec
	s_waitcnt vmcnt(0) lgkmcnt(0)
	v_add_u32_e32 v26, v10, v25
	v_add_u32_e32 v26, v26, v11
	v_add_u32_e32 v26, v26, v12
	v_add_u32_e32 v26, v26, v13
	v_add_u32_e32 v26, v26, v14
	v_add_u32_e32 v26, v26, v15
	v_add_u32_e32 v26, v26, v16
	v_add_u32_e32 v26, v26, v17
	v_add_u32_e32 v26, v26, v18
	v_add_u32_e32 v26, v26, v19
	v_add_u32_e32 v26, v26, v20
	v_add_u32_e32 v26, v26, v21
	v_add_u32_e32 v26, v26, v22
	v_add_u32_e32 v26, v26, v23
	v_add_u32_e32 v26, v26, v24
	v_cmp_ne_u32_e32 vcc, s18, v26
	s_and_saveexec_b64 s[8:9], vcc
	s_cbranch_execz .LBB0_88
	s_and_b32 s12, s19, 0xff
	s_mov_b64 s[10:11], -1
	s_cmp_eq_u32 s12, 0
	s_mov_b64 s[14:15], -1
	s_mov_b64 s[12:13], -1
	s_sleep 1
	s_cbranch_scc1 .LBB0_92
	s_and_saveexec_b64 s[16:17], s[14:15]
	s_cbranch_execz .LBB0_87
	s_branch .LBB0_95
.LBB0_92:
	global_load_dword v26, v[0:1], off offset:512 sc1
	s_mov_b64 s[14:15], 0
	s_waitcnt vmcnt(0) lgkmcnt(0)
	v_cmp_eq_u32_e32 vcc, 0, v26
	s_and_saveexec_b64 s[16:17], vcc
	s_cmp_lt_u32 s19, 0x400001
	s_cselect_b64 s[14:15], -1, 0
	s_xor_b64 s[12:13], exec, -1
	s_and_b64 s[14:15], s[14:15], exec
	s_or_b64 exec, exec, s[16:17]
	s_and_saveexec_b64 s[16:17], s[14:15]
	s_cbranch_execz .LBB0_87

; __device__ __forceinline__ unsigned xb_ld(unsigned* p)              { return __hip_atomic_load(p, __ATOMIC_RELAXED, __HIP_MEMORY_SCOPE_AGENT); }
; __device__ __forceinline__ void xcd_barrier_complete(unsigned* bar, unsigned x, unsigned& nloc, unsigned& nx) {
;     ...
;         __builtin_amdgcn_s_sleep(1);
;         if ((++sp & 255u) == 0u) { if (xb_ld(&bar[XB_TMO])) break; if (sp > XB_SPIN_CAP) { atomicAdd(&bar[XB_TMO], 1u); break; } }
;     }
;     nloc = mine > 0u ? mine : 1u; nx = cnt > 0u ? cnt : 1u;
; }
.LBB0_96:
	s_or_b64 exec, exec, s[0:1]
	s_xor_b64 s[0:1], s[2:3], -1
	s_and_saveexec_b64 s[2:3], s[0:1]
	s_xor_b64 s[0:1], exec, s[2:3]
	s_cbranch_execz .LBB0_98
	v_mov_b32_e32 v2, 1
	v_mov_b64_e32 v[0:1], s[34:35]
	global_atomic_add v[0:1], v2, off offset:512

; __device__ __forceinline__ unsigned xb_ld(unsigned* p)              { return __hip_atomic_load(p, __ATOMIC_RELAXED, __HIP_MEMORY_SCOPE_AGENT); }
; __device__ __forceinline__ unsigned xb_add(unsigned* p, unsigned v) { return __hip_atomic_fetch_add(p, v, __ATOMIC_RELAXED, __HIP_MEMORY_SCOPE_AGENT); }
; #define XB_SPIN(cond, bar) do { unsigned _sp = 0; while (cond) { __builtin_amdgcn_s_sleep(1); \
;     if ((++_sp & 255u) == 0u) { if (xb_ld(&(bar)[XB_TMO])) break; if (_sp > XB_SPIN_CAP) { atomicAdd(&(bar)[XB_TMO], 1u); break; } } } } while (0)
; __device__ __forceinline__ void xcd_barrier(const int wv, const XcdBarrier& b) {
;     ...
;         unsigned nloc = b.st[0], nx = b.st[1];
;         if (nloc == 0u) { xcd_barrier_complete(bar, b.x, nloc, nx); b.st[0] = nloc; b.st[1] = nx; }
;         const unsigned old = xb_add(&bar[XB_XSUB(b.x)], 1u);
;         const unsigned gen = old / nloc;
;         if (old + 1u == (gen + 1u) * nloc) {
;     ...
;             XB_SPIN(xb_ld(&bar[XB_XGEN(b.x)]) == gen, bar);
.LBB0_99:
	s_lshl_b32 s0, s36, 6
	s_lshl_b32 s1, s36, 8
	s_add_u32 s25, s34, s1
	s_addc_u32 s24, s35, 0
	v_mov_b32_e32 v1, s25
	v_add_co_u32_e32 v4, vcc, 0x1000, v1
	v_mov_b32_e32 v1, s24
	s_nop 0
	v_addc_co_u32_e32 v5, vcc, 0, v1, vcc
	v_mov_b32_e32 v1, 1
	global_atomic_add v1, v[4:5], v1, off offset:1024 sc0
	v_cvt_f32_u32_e32 v3, v2
	v_sub_u32_e32 v4, 0, v2
	s_mov_b32 s1, 0
	v_rcp_iflag_f32_e32 v3, v3
	s_nop 0
	v_mul_f32_e32 v3, 0x4f7ffffe, v3
	v_cvt_u32_f32_e32 v3, v3
	v_mul_lo_u32 v4, v4, v3
	v_mul_hi_u32 v4, v3, v4
	v_add_u32_e32 v3, v3, v4
	s_waitcnt vmcnt(0) lgkmcnt(0)
	v_mul_hi_u32 v3, v1, v3
	v_mul_lo_u32 v5, v3, v2
	v_add_u32_e32 v4, 1, v1
	v_sub_u32_e32 v1, v1, v5
	v_add_u32_e32 v6, 1, v3
	v_cmp_ge_u32_e32 vcc, v1, v2
	v_sub_u32_e32 v5, v1, v2
	s_nop 0
	v_cndmask_b32_e32 v3, v3, v6, vcc
	v_cndmask_b32_e32 v1, v1, v5, vcc
	v_add_u32_e32 v5, 1, v3
	v_cmp_ge_u32_e32 vcc, v1, v2
	s_nop 1
	v_cndmask_b32_e32 v1, v3, v5, vcc
	v_mad_u64_u32 v[2:3], s[2:3], v2, v1, v[2:3]
	v_cmp_ne_u32_e32 vcc, v4, v2
	s_and_saveexec_b64 s[2:3], vcc
	s_xor_b64 s[2:3], exec, s[2:3]
	s_cbranch_execz .LBB0_112
	v_mov_b32_e32 v0, s25
	v_add_co_u32_e32 v2, vcc, 0x2000, v0
	v_mov_b32_e32 v0, s24
	s_nop 0
	v_addc_co_u32_e32 v3, vcc, 0, v0, vcc
	global_load_dword v0, v[2:3], off offset:1024 sc1
	s_add_u32 s6, s25, 0x2400
	s_addc_u32 s7, s24, 0
	s_waitcnt vmcnt(0) lgkmcnt(0)
	v_cmp_eq_u32_e32 vcc, v0, v1
	s_and_saveexec_b64 s[4:5], vcc
	s_cbranch_execz .LBB0_111
	s_mov_b32 s22, 1
	s_mov_b64 s[8:9], 0
	s_branch .LBB0_103

; __device__ __forceinline__ unsigned xb_ld(unsigned* p)              { return __hip_atomic_load(p, __ATOMIC_RELAXED, __HIP_MEMORY_SCOPE_AGENT); }
; #define XB_SPIN(cond, bar) do { unsigned _sp = 0; while (cond) { __builtin_amdgcn_s_sleep(1); \
;     if ((++_sp & 255u) == 0u) { if (xb_ld(&(bar)[XB_TMO])) break; if (_sp > XB_SPIN_CAP) { atomicAdd(&(bar)[XB_TMO], 1u); break; } } } } while (0)
; __device__ __forceinline__ void xcd_barrier(const int wv, const XcdBarrier& b) {
;     ...
;             XB_SPIN(xb_ld(&bar[XB_XGEN(b.x)]) == gen, bar);
.LBB0_103:
	s_and_b32 s16, s22, 0xff
	s_mov_b64 s[14:15], -1
	s_cmp_lg_u32 s16, 0
	s_mov_b64 s[16:17], -1
	s_sleep 1
	s_cbranch_scc1 .LBB0_107
	v_mov_b64_e32 v[2:3], s[34:35]
	global_load_dword v0, v[2:3], off offset:512 sc1
	s_mov_b64 s[16:17], 0
	s_mov_b64 s[18:19], -1
	s_waitcnt vmcnt(0) lgkmcnt(0)
	v_cmp_eq_u32_e32 vcc, 0, v0
	s_and_saveexec_b64 s[20:21], vcc
	s_cmp_lt_u32 s22, 0x400001
	s_cselect_b64 s[16:17], -1, 0
	s_xor_b64 s[18:19], exec, -1
	s_and_b64 s[16:17], s[16:17], exec
	s_or_b64 exec, exec, s[20:21]
.LBB0_107:
	s_andn2_b64 s[12:13], s[12:13], exec
	s_and_b64 s[18:19], s[18:19], exec
	s_or_b64 s[12:13], s[12:13], s[18:19]
	s_and_saveexec_b64 s[18:19], s[16:17]
	s_cbranch_execz .LBB0_102
	v_mov_b64_e32 v[2:3], s[6:7]
	global_load_dword v0, v[2:3], off sc1
	s_add_i32 s22, s22, 1
	s_or_b64 s[12:13], s[12:13], exec
	s_waitcnt vmcnt(0) lgkmcnt(0)
	v_cmp_ne_u32_e32 vcc, v0, v1
	s_orn2_b64 s[14:15], vcc, exec
	s_branch .LBB0_102
.LBB0_109:
	s_or_b64 exec, exec, s[8:9]
	s_xor_b64 s[6:7], s[10:11], -1
	s_and_saveexec_b64 s[8:9], s[6:7]
	s_xor_b64 s[8:9], exec, s[8:9]
	s_cbranch_execz .LBB0_111
	v_mov_b32_e32 v2, 1
	v_mov_b64_e32 v[0:1], s[34:35]
	global_atomic_add v[0:1], v2, off offset:512

; __device__ __forceinline__ unsigned xb_ld(unsigned* p)              { return __hip_atomic_load(p, __ATOMIC_RELAXED, __HIP_MEMORY_SCOPE_AGENT); }
; __device__ __forceinline__ unsigned xb_add(unsigned* p, unsigned v) { return __hip_atomic_fetch_add(p, v, __ATOMIC_RELAXED, __HIP_MEMORY_SCOPE_AGENT); }
; #define XB_SPIN(cond, bar) do { unsigned _sp = 0; while (cond) { __builtin_amdgcn_s_sleep(1); \
;     if ((++_sp & 255u) == 0u) { if (xb_ld(&(bar)[XB_TMO])) break; if (_sp > XB_SPIN_CAP) { atomicAdd(&(bar)[XB_TMO], 1u); break; } } } } while (0)
; __device__ __forceinline__ void xcd_barrier(const int wv, const XcdBarrier& b) {
;     ...
;         if (old + 1u == (gen + 1u) * nloc) {
;             __builtin_amdgcn_fence(__ATOMIC_RELEASE, "agent");
;             asm volatile("s_waitcnt vmcnt(0)" ::: "memory");
;             const unsigned og = xb_add(&bar[XB_TOP], 1u);
;             const unsigned tg = og / nx;
;             if (og + 1u == (tg + 1u) * nx) xb_add(&bar[XB_TOPGEN], 1u);
;             else XB_SPIN(xb_ld(&bar[XB_TOPGEN]) == tg, bar);
.LBB0_112:
	s_andn2_saveexec_b64 s[2:3], s[2:3]
	s_cbranch_execz .LBB0_128
	v_mov_b32_e32 v1, s34
	v_add_co_u32_e32 v2, vcc, 0x3000, v1
	v_mov_b32_e32 v1, s35
	buffer_wbl2 sc1
	s_waitcnt vmcnt(0)
	v_addc_co_u32_e32 v3, vcc, 0, v1, vcc
	v_mov_b32_e32 v1, 1
	global_atomic_add v1, v[2:3], v1, off offset:1024 sc0
	v_cvt_f32_u32_e32 v2, v0
	v_sub_u32_e32 v3, 0, v0
	s_add_u32 s4, s34, 0x3500
	s_addc_u32 s5, s35, 0
	v_rcp_iflag_f32_e32 v2, v2
	s_mov_b64 s[8:9], -1
	v_mul_f32_e32 v2, 0x4f7ffffe, v2
	v_cvt_u32_f32_e32 v2, v2
	v_mul_lo_u32 v3, v3, v2
	v_mul_hi_u32 v3, v2, v3
	v_add_u32_e32 v2, v2, v3
	s_waitcnt vmcnt(0) lgkmcnt(0)
	v_mul_hi_u32 v2, v1, v2
	v_mul_lo_u32 v4, v2, v0
	v_add_u32_e32 v3, 1, v1
	v_sub_u32_e32 v1, v1, v4
	v_add_u32_e32 v5, 1, v2
	v_cmp_ge_u32_e32 vcc, v1, v0
	v_sub_u32_e32 v4, v1, v0
	s_nop 0
	v_cndmask_b32_e32 v2, v2, v5, vcc
	v_cndmask_b32_e32 v1, v1, v4, vcc
	v_add_u32_e32 v4, 1, v2
	v_cmp_ge_u32_e32 vcc, v1, v0
	s_nop 1
	v_cndmask_b32_e32 v2, v2, v4, vcc
	v_mad_u64_u32 v[0:1], s[6:7], v0, v2, v[0:1]
	v_cmp_ne_u32_e32 vcc, v3, v0
	v_mov_b64_e32 v[0:1], s[4:5]
	s_and_saveexec_b64 s[6:7], vcc
	s_cbranch_execz .LBB0_125
	v_mov_b64_e32 v[0:1], s[4:5]
	global_load_dword v0, v[0:1], off sc1
	s_mov_b64 s[12:13], 0
	s_waitcnt vmcnt(0) lgkmcnt(0)
	v_cmp_eq_u32_e32 vcc, v0, v2
	s_and_saveexec_b64 s[10:11], vcc
	s_cbranch_execz .LBB0_124
	s_add_u32 s8, s34, 0x200
	s_addc_u32 s9, s35, 0
	s_mov_b32 s26, 1
	s_branch .LBB0_117

; __device__ __forceinline__ unsigned xb_ld(unsigned* p)              { return __hip_atomic_load(p, __ATOMIC_RELAXED, __HIP_MEMORY_SCOPE_AGENT); }
; #define XB_SPIN(cond, bar) do { unsigned _sp = 0; while (cond) { __builtin_amdgcn_s_sleep(1); \
;     if ((++_sp & 255u) == 0u) { if (xb_ld(&(bar)[XB_TMO])) break; if (_sp > XB_SPIN_CAP) { atomicAdd(&(bar)[XB_TMO], 1u); break; } } } } while (0)
; __device__ __forceinline__ void xcd_barrier(const int wv, const XcdBarrier& b) {
;     ...
;             else XB_SPIN(xb_ld(&bar[XB_TOPGEN]) == tg, bar);
.LBB0_119:
	v_mov_b64_e32 v[0:1], s[8:9]
	global_load_dword v0, v[0:1], off sc1
	s_mov_b64 s[18:19], 0
	s_mov_b64 s[16:17], -1
	s_waitcnt vmcnt(0) lgkmcnt(0)
	v_cmp_eq_u32_e32 vcc, 0, v0
	s_and_saveexec_b64 s[20:21], vcc
	s_cmp_lt_u32 s26, 0x400001
	s_cselect_b64 s[18:19], -1, 0
	s_xor_b64 s[16:17], exec, -1
	s_and_b64 s[18:19], s[18:19], exec
	s_or_b64 exec, exec, s[20:21]
	s_mov_b64 s[20:21], -1
	s_and_saveexec_b64 s[22:23], s[18:19]
	s_cbranch_execz .LBB0_116
.LBB0_122:
	v_mov_b64_e32 v[0:1], s[4:5]
	global_load_dword v0, v[0:1], off sc1
	s_add_i32 s26, s26, 1
	s_or_b64 s[16:17], s[16:17], exec
	s_waitcnt vmcnt(0) lgkmcnt(0)
	v_cmp_ne_u32_e32 vcc, v0, v2
	s_orn2_b64 s[20:21], vcc, exec
	s_branch .LBB0_116

; __device__ __forceinline__ unsigned xb_ld(unsigned* p)              { return __hip_atomic_load(p, __ATOMIC_RELAXED, __HIP_MEMORY_SCOPE_AGENT); }
; __device__ __forceinline__ unsigned xb_add(unsigned* p, unsigned v) { return __hip_atomic_fetch_add(p, v, __ATOMIC_RELAXED, __HIP_MEMORY_SCOPE_AGENT); }
; #define XB_SPIN(cond, bar) do { unsigned _sp = 0; while (cond) { __builtin_amdgcn_s_sleep(1); \
;     if ((++_sp & 255u) == 0u) { if (xb_ld(&(bar)[XB_TMO])) break; if (_sp > XB_SPIN_CAP) { atomicAdd(&(bar)[XB_TMO], 1u); break; } } } } while (0)
; __device__ __forceinline__ void xcd_barrier(const int wv, const XcdBarrier& b) {
;     ...
;             if (og + 1u == (tg + 1u) * nx) xb_add(&bar[XB_TOPGEN], 1u);
;             else XB_SPIN(xb_ld(&bar[XB_TOPGEN]) == tg, bar);
;             __builtin_amdgcn_fence(__ATOMIC_ACQUIRE, "agent");
;             xb_add(&bar[XB_XGEN(b.x)], 1u);
;             asm volatile("s_waitcnt vmcnt(0)" ::: "memory");
.LBB0_125:
	s_or_b64 exec, exec, s[6:7]
	s_and_saveexec_b64 s[4:5], s[8:9]
	s_cbranch_execz .LBB0_127
	v_mov_b32_e32 v2, 1
	global_atomic_add v[0:1], v2, off
.LBB0_127:
	s_or_b64 exec, exec, s[4:5]
	v_mov_b32_e32 v0, s25
	v_add_co_u32_e32 v0, vcc, 0x2000, v0
	v_mov_b32_e32 v1, s24
	s_nop 0
	v_addc_co_u32_e32 v1, vcc, 0, v1, vcc
	v_mov_b32_e32 v2, 1
	s_waitcnt vmcnt(0) lgkmcnt(0)
	buffer_inv sc1
	global_atomic_add v[0:1], v2, off offset:1024
	s_waitcnt vmcnt(0)

; __device__ __forceinline__ unsigned xb_add(unsigned* p, unsigned v) { return __hip_atomic_fetch_add(p, v, __ATOMIC_RELAXED, __HIP_MEMORY_SCOPE_AGENT); }
; __device__ __forceinline__ void xcd_barrier(const int wv, const XcdBarrier& b) {
;     ...
;             __builtin_amdgcn_fence(__ATOMIC_ACQUIRE, "agent");
;             xb_add(&bar[XB_XGEN(b.x)], 1u);
;             asm volatile("s_waitcnt vmcnt(0)" ::: "memory");
.LBB0_130:
	s_or_b64 exec, exec, s[2:3]
	v_add_co_u32_e32 v2, vcc, 0x2000, v2
	s_waitcnt vmcnt(0) lgkmcnt(0)
	buffer_inv sc1
	v_addc_co_u32_e32 v3, vcc, 0, v3, vcc
	global_atomic_add v[2:3], v184, off offset:1024
	s_waitcnt vmcnt(0)

; __device__ __forceinline__ unsigned xb_ld(unsigned* p)              { return __hip_atomic_load(p, __ATOMIC_RELAXED, __HIP_MEMORY_SCOPE_AGENT); }
; __device__ __forceinline__ void xcd_barrier_complete(unsigned* bar, unsigned x, unsigned& nloc, unsigned& nx) {
;     ...
;     for (;;) {
;         sum = 0u; cnt = 0u; mine = 0u;
; #pragma unroll
;         for (unsigned j = 0; j < 16; ++j) { const unsigned c = xb_ld(&bar[XB_XCNT(j)]); sum += c; cnt += (c > 0u) ? 1u : 0u; mine = (j == x) ? c : mine; }
;         if (sum == G) break;
;         __builtin_amdgcn_s_sleep(1);
;         if ((++sp & 255u) == 0u) { if (xb_ld(&bar[XB_TMO])) break; if (sp > XB_SPIN_CAP) { atomicAdd(&bar[XB_TMO], 1u); break; } }
;     }
;     nloc = mine > 0u ? mine : 1u; nx = cnt > 0u ? cnt : 1u;
; }
.LBB0_271:
	v_mov_b64_e32 v[12:13], s[2:3]
	global_load_dword v2, v[12:13], off offset:1024 sc1
	global_load_dword v1, v[12:13], off offset:1280 sc1
	global_load_dword v3, v[12:13], off offset:1536 sc1
	s_or_b64 s[18:19], s[18:19], exec
	s_or_b64 s[16:17], s[16:17], exec
	s_waitcnt vmcnt(0) lgkmcnt(0)
	v_add_u32_e32 v4, v1, v2
	v_add_u32_e32 v5, v4, v3
	global_load_dword v4, v[12:13], off offset:1792 sc1
	s_waitcnt vmcnt(0) lgkmcnt(0)
	v_add_u32_e32 v6, v5, v4
	global_load_dword v5, v[12:13], off offset:2048 sc1
	s_waitcnt vmcnt(0) lgkmcnt(0)
	v_add_u32_e32 v7, v6, v5
	global_load_dword v6, v[12:13], off offset:2304 sc1
	s_waitcnt vmcnt(0) lgkmcnt(0)
	v_add_u32_e32 v8, v7, v6
	global_load_dword v7, v[12:13], off offset:2560 sc1
	s_waitcnt vmcnt(0) lgkmcnt(0)
	v_add_u32_e32 v9, v8, v7
	global_load_dword v8, v[12:13], off offset:2816 sc1
	s_waitcnt vmcnt(0) lgkmcnt(0)
	v_add_u32_e32 v10, v9, v8
	global_load_dword v9, v[12:13], off offset:3072 sc1
	s_waitcnt vmcnt(0) lgkmcnt(0)
	v_add_u32_e32 v11, v10, v9
	global_load_dword v10, v[12:13], off offset:3328 sc1
	s_waitcnt vmcnt(0) lgkmcnt(0)
	v_add_u32_e32 v14, v11, v10
	global_load_dword v11, v[12:13], off offset:3584 sc1
	s_waitcnt vmcnt(0) lgkmcnt(0)
	v_add_u32_e32 v14, v14, v11
	global_load_dword v12, v[12:13], off offset:3840 sc1
	s_waitcnt vmcnt(0) lgkmcnt(0)
	v_add_u32_e32 v16, v14, v12
	v_mov_b64_e32 v[14:15], s[4:5]
	global_load_dword v13, v[14:15], off sc1
	v_mov_b64_e32 v[14:15], s[6:7]
	global_load_dword v14, v[14:15], off sc1
	s_waitcnt vmcnt(0) lgkmcnt(0)
	v_add_u32_e32 v16, v16, v13
	v_add_u32_e32 v18, v16, v14
	v_mov_b64_e32 v[16:17], s[8:9]
	global_load_dword v15, v[16:17], off sc1
	v_mov_b64_e32 v[16:17], s[10:11]
	global_load_dword v16, v[16:17], off sc1
	s_waitcnt vmcnt(0) lgkmcnt(0)
	v_add_u32_e32 v18, v18, v15
	v_add_u32_e32 v17, v18, v16
	v_cmp_ne_u32_e32 vcc, s61, v17
	s_and_saveexec_b64 s[20:21], vcc
	s_cbranch_execz .LBB0_270
	s_and_b32 s24, s30, 0xff
	s_mov_b64 s[22:23], -1
	s_cmp_eq_u32 s24, 0
	s_mov_b64 s[26:27], -1
	s_mov_b64 s[24:25], -1
	s_sleep 1
	s_cbranch_scc1 .LBB0_274
	s_and_saveexec_b64 s[28:29], s[26:27]
	s_cbranch_execz .LBB0_269
	s_branch .LBB0_277
.LBB0_274:
	v_mov_b64_e32 v[18:19], s[2:3]
	global_load_dword v17, v[18:19], off offset:512 sc1
	s_mov_b64 s[26:27], 0
	s_waitcnt vmcnt(0) lgkmcnt(0)
	v_cmp_eq_u32_e32 vcc, 0, v17
	s_and_saveexec_b64 s[28:29], vcc
	s_cmp_lt_u32 s30, 0x400001
	s_cselect_b64 s[26:27], -1, 0
	s_xor_b64 s[24:25], exec, -1
	s_and_b64 s[26:27], s[26:27], exec
	s_or_b64 exec, exec, s[28:29]
	s_and_saveexec_b64 s[28:29], s[26:27]
	s_cbranch_execz .LBB0_269

; __device__ __forceinline__ unsigned xb_ld(unsigned* p)              { return __hip_atomic_load(p, __ATOMIC_RELAXED, __HIP_MEMORY_SCOPE_AGENT); }
; __device__ __forceinline__ void xcd_barrier_complete(unsigned* bar, unsigned x, unsigned& nloc, unsigned& nx) {
;     ...
;         __builtin_amdgcn_s_sleep(1);
;         if ((++sp & 255u) == 0u) { if (xb_ld(&bar[XB_TMO])) break; if (sp > XB_SPIN_CAP) { atomicAdd(&bar[XB_TMO], 1u); break; } }
;     }
;     nloc = mine > 0u ? mine : 1u; nx = cnt > 0u ? cnt : 1u;
.LBB0_278:
	s_or_b64 exec, exec, s[12:13]
	s_xor_b64 s[4:5], s[14:15], -1
	s_and_saveexec_b64 s[6:7], s[4:5]
	s_xor_b64 s[4:5], exec, s[6:7]
	s_cbranch_execz .LBB0_280
	v_mov_b64_e32 v[18:19], s[2:3]
	global_atomic_add v[18:19], v184, off offset:512

; __device__ __forceinline__ unsigned xb_ld(unsigned* p)              { return __hip_atomic_load(p, __ATOMIC_RELAXED, __HIP_MEMORY_SCOPE_AGENT); }
; __device__ __forceinline__ unsigned xb_add(unsigned* p, unsigned v) { return __hip_atomic_fetch_add(p, v, __ATOMIC_RELAXED, __HIP_MEMORY_SCOPE_AGENT); }
; #define XB_SPIN(cond, bar) do { unsigned _sp = 0; while (cond) { __builtin_amdgcn_s_sleep(1); \
;     if ((++_sp & 255u) == 0u) { if (xb_ld(&(bar)[XB_TMO])) break; if (_sp > XB_SPIN_CAP) { atomicAdd(&(bar)[XB_TMO], 1u); break; } } } } while (0)
; __device__ __forceinline__ void xcd_barrier(const int wv, const XcdBarrier& b) {
;     ...
;         if (nloc == 0u) { xcd_barrier_complete(bar, b.x, nloc, nx); b.st[0] = nloc; b.st[1] = nx; }
;         const unsigned old = xb_add(&bar[XB_XSUB(b.x)], 1u);
;         const unsigned gen = old / nloc;
;         if (old + 1u == (gen + 1u) * nloc) {
;             __builtin_amdgcn_fence(__ATOMIC_RELEASE, "agent");
;             asm volatile("s_waitcnt vmcnt(0)" ::: "memory");
;             const unsigned og = xb_add(&bar[XB_TOP], 1u);
;             const unsigned tg = og / nx;
;             if (og + 1u == (tg + 1u) * nx) xb_add(&bar[XB_TOPGEN], 1u);
;             else XB_SPIN(xb_ld(&bar[XB_TOPGEN]) == tg, bar);
.LBB0_281:
	v_lshl_add_u64 v[2:3], v[178:179], 2, s[2:3]
	v_add_co_u32_e32 v8, vcc, 0x1000, v2
	v_cvt_f32_u32_e32 v1, v6
	s_nop 0
	v_addc_co_u32_e32 v9, vcc, 0, v3, vcc
	global_atomic_add v5, v[8:9], v184, off offset:1024 sc0
	v_rcp_iflag_f32_e32 v1, v1
	v_sub_u32_e32 v7, 0, v6
	v_mul_f32_e32 v1, 0x4f7ffffe, v1
	v_cvt_u32_f32_e32 v1, v1
	v_mul_lo_u32 v7, v7, v1
	v_mul_hi_u32 v7, v1, v7
	v_add_u32_e32 v1, v1, v7
	s_waitcnt vmcnt(0) lgkmcnt(0)
	v_mul_hi_u32 v1, v5, v1
	v_mul_lo_u32 v7, v1, v6
	v_sub_u32_e32 v7, v5, v7
	v_cmp_ge_u32_e32 vcc, v7, v6
	v_add_u32_e32 v8, 1, v1
	v_add_u32_e32 v5, 1, v5
	v_cndmask_b32_e32 v1, v1, v8, vcc
	v_sub_u32_e32 v8, v7, v6
	v_cndmask_b32_e32 v7, v7, v8, vcc
	v_cmp_ge_u32_e32 vcc, v7, v6
	v_add_u32_e32 v7, 1, v1
	s_nop 0
	v_cndmask_b32_e32 v1, v1, v7, vcc
	v_mad_u64_u32 v[6:7], s[4:5], v6, v1, v[6:7]
	v_cmp_ne_u32_e32 vcc, v5, v6
	s_and_saveexec_b64 s[4:5], vcc
	s_xor_b64 s[4:5], exec, s[4:5]
	s_cbranch_execz .LBB0_294
	v_add_co_u32_e32 v4, vcc, 0x2400, v2
	s_nop 1
	v_addc_co_u32_e32 v5, vcc, 0, v3, vcc
	s_nop 0
	v_readfirstlane_b32 s98, v4
	v_readfirstlane_b32 s99, v5
	v_readfirstlane_b32 s100, v1
	s_mov_b32 s101, 0x40000
.LBB0_294:
	s_andn2_saveexec_b64 s[4:5], s[4:5]
	s_cbranch_execz .LBB0_310
	v_mov_b32_e32 v1, s2
	v_add_co_u32_e32 v6, vcc, 0x3000, v1
	v_mov_b32_e32 v1, s3
	buffer_wbl2 sc1
	s_waitcnt vmcnt(0)
	v_addc_co_u32_e32 v7, vcc, 0, v1, vcc
	global_atomic_add v5, v[6:7], v184, off offset:1024 sc0
	v_cvt_f32_u32_e32 v1, v4
	v_sub_u32_e32 v6, 0, v4
	s_mov_b64 s[8:9], -1
	v_rcp_iflag_f32_e32 v1, v1
	s_nop 0
	v_mul_f32_e32 v1, 0x4f7ffffe, v1
	v_cvt_u32_f32_e32 v1, v1
	v_mul_lo_u32 v6, v6, v1
	v_mul_hi_u32 v6, v1, v6
	v_add_u32_e32 v1, v1, v6
	s_waitcnt vmcnt(0) lgkmcnt(0)
	v_mul_hi_u32 v1, v5, v1
	v_mul_lo_u32 v6, v1, v4
	v_sub_u32_e32 v6, v5, v6
	v_cmp_ge_u32_e32 vcc, v6, v4
	v_add_u32_e32 v7, 1, v1
	s_nop 0
	v_cndmask_b32_e32 v1, v1, v7, vcc
	v_sub_u32_e32 v7, v6, v4
	v_cndmask_b32_e32 v6, v6, v7, vcc
	v_cmp_ge_u32_e32 vcc, v6, v4
	v_add_u32_e32 v6, 1, v1
	s_nop 0
	v_cndmask_b32_e32 v1, v1, v6, vcc
	v_add_u32_e32 v6, 1, v5
	v_mad_u64_u32 v[4:5], s[4:5], v4, v1, v[4:5]
	s_add_u32 s4, s2, 0x3500
	s_addc_u32 s5, s3, 0
	v_cmp_ne_u32_e32 vcc, v6, v4
	v_mov_b64_e32 v[4:5], s[4:5]
	s_and_saveexec_b64 s[6:7], vcc
	s_cbranch_execz .LBB0_307
	v_mov_b64_e32 v[4:5], s[4:5]
	global_load_dword v4, v[4:5], off sc1
	s_mov_b64 s[12:13], 0
	s_waitcnt vmcnt(0) lgkmcnt(0)
	v_cmp_eq_u32_e32 vcc, v4, v1
	s_and_saveexec_b64 s[10:11], vcc
	s_cbranch_execz .LBB0_306
	s_add_u32 s8, s2, 0x200
	s_addc_u32 s9, s3, 0
	s_mov_b32 s22, 1
	s_mov_b64 s[2:3], 0
	s_branch .LBB0_299

; __device__ __forceinline__ unsigned xb_ld(unsigned* p)              { return __hip_atomic_load(p, __ATOMIC_RELAXED, __HIP_MEMORY_SCOPE_AGENT); }
; #define XB_SPIN(cond, bar) do { unsigned _sp = 0; while (cond) { __builtin_amdgcn_s_sleep(1); \
;     if ((++_sp & 255u) == 0u) { if (xb_ld(&(bar)[XB_TMO])) break; if (_sp > XB_SPIN_CAP) { atomicAdd(&(bar)[XB_TMO], 1u); break; } } } } while (0)
; __device__ __forceinline__ void xcd_barrier(const int wv, const XcdBarrier& b) {
;     ...
;             else XB_SPIN(xb_ld(&bar[XB_TOPGEN]) == tg, bar);
.LBB0_301:
	v_mov_b64_e32 v[4:5], s[8:9]
	global_load_dword v4, v[4:5], off sc1
	s_mov_b64 s[18:19], 0
	s_mov_b64 s[16:17], -1
	s_waitcnt vmcnt(0) lgkmcnt(0)
	v_cmp_eq_u32_e32 vcc, 0, v4
	s_and_saveexec_b64 s[20:21], vcc
	s_cmp_lt_u32 s22, 0x400001
	s_cselect_b64 s[18:19], -1, 0
	s_xor_b64 s[16:17], exec, -1
	s_and_b64 s[18:19], s[18:19], exec
	s_or_b64 exec, exec, s[20:21]
	s_and_saveexec_b64 s[20:21], s[18:19]
	s_cbranch_execz .LBB0_298
.LBB0_304:
	v_mov_b64_e32 v[4:5], s[4:5]
	global_load_dword v4, v[4:5], off sc1
	s_add_i32 s22, s22, 1
	s_or_b64 s[16:17], s[16:17], exec
	s_waitcnt vmcnt(0) lgkmcnt(0)
	v_cmp_ne_u32_e32 vcc, v4, v1
	s_orn2_b64 s[14:15], vcc, exec
	s_branch .LBB0_298

; __device__ __forceinline__ unsigned xb_ld(unsigned* p)              { return __hip_atomic_load(p, __ATOMIC_RELAXED, __HIP_MEMORY_SCOPE_AGENT); }
; __device__ __forceinline__ unsigned xb_add(unsigned* p, unsigned v) { return __hip_atomic_fetch_add(p, v, __ATOMIC_RELAXED, __HIP_MEMORY_SCOPE_AGENT); }
; #define XB_SPIN(cond, bar) do { unsigned _sp = 0; while (cond) { __builtin_amdgcn_s_sleep(1); \
;     if ((++_sp & 255u) == 0u) { if (xb_ld(&(bar)[XB_TMO])) break; if (_sp > XB_SPIN_CAP) { atomicAdd(&(bar)[XB_TMO], 1u); break; } } } } while (0)
; __device__ __forceinline__ void xcd_barrier(const int wv, const XcdBarrier& b) {
;     ...
;         if (nloc == 0u) { xcd_barrier_complete(bar, b.x, nloc, nx); b.st[0] = nloc; b.st[1] = nx; }
;         const unsigned old = xb_add(&bar[XB_XSUB(b.x)], 1u);
;         const unsigned gen = old / nloc;
;         if (old + 1u == (gen + 1u) * nloc) {
;     ...
;             XB_SPIN(xb_ld(&bar[XB_XGEN(b.x)]) == gen, bar);
.LBB0_534:
	v_lshl_add_u64 v[2:3], v[178:179], 2, s[2:3]
	v_add_co_u32_e32 v8, vcc, 0x1000, v2
	v_cvt_f32_u32_e32 v1, v6
	s_nop 0
	v_addc_co_u32_e32 v9, vcc, 0, v3, vcc
	global_atomic_add v5, v[8:9], v184, off offset:1024 sc0
	v_rcp_iflag_f32_e32 v1, v1
	v_sub_u32_e32 v7, 0, v6
	v_mul_f32_e32 v1, 0x4f7ffffe, v1
	v_cvt_u32_f32_e32 v1, v1
	v_mul_lo_u32 v7, v7, v1
	v_mul_hi_u32 v7, v1, v7
	v_add_u32_e32 v1, v1, v7
	s_waitcnt vmcnt(0) lgkmcnt(0)
	v_mul_hi_u32 v1, v5, v1
	v_mul_lo_u32 v7, v1, v6
	v_sub_u32_e32 v7, v5, v7
	v_cmp_ge_u32_e32 vcc, v7, v6
	v_add_u32_e32 v8, 1, v1
	v_add_u32_e32 v5, 1, v5
	v_cndmask_b32_e32 v1, v1, v8, vcc
	v_sub_u32_e32 v8, v7, v6
	v_cndmask_b32_e32 v7, v7, v8, vcc
	v_cmp_ge_u32_e32 vcc, v7, v6
	v_add_u32_e32 v7, 1, v1
	s_nop 0
	v_cndmask_b32_e32 v1, v1, v7, vcc
	v_mad_u64_u32 v[6:7], s[4:5], v6, v1, v[6:7]
	v_cmp_ne_u32_e32 vcc, v5, v6
	s_and_saveexec_b64 s[4:5], vcc
	s_xor_b64 s[4:5], exec, s[4:5]
	s_cbranch_execz .LBB0_547
	s_cmp_eq_u32 s79, 3
	s_cbranch_scc1 .Lrcip_full
	v_add_co_u32_e32 v4, vcc, 0x2400, v2
	s_nop 1
	v_addc_co_u32_e32 v5, vcc, 0, v3, vcc
	s_nop 0
	v_readfirstlane_b32 s98, v4
	v_readfirstlane_b32 s99, v5
	v_readfirstlane_b32 s100, v1
	s_mov_b32 s101, 0x40000
	s_branch .LBB0_547
.Lrcip_full:
	v_add_co_u32_e32 v4, vcc, 0x2000, v2
	s_nop 1
	v_addc_co_u32_e32 v5, vcc, 0, v3, vcc
	global_load_dword v4, v[4:5], off offset:1024 sc1
	s_waitcnt vmcnt(0) lgkmcnt(0)
	v_cmp_eq_u32_e32 vcc, v4, v1
	s_and_saveexec_b64 s[6:7], vcc
	s_cbranch_execz .LBB0_546
	s_mov_b64 s[8:9], 0x2400
	v_lshl_add_u64 v[2:3], v[2:3], 0, s[8:9]
	s_mov_b32 s22, 1
	s_mov_b64 s[8:9], 0
	s_branch .LBB0_538

; __device__ __forceinline__ unsigned xb_ld(unsigned* p)              { return __hip_atomic_load(p, __ATOMIC_RELAXED, __HIP_MEMORY_SCOPE_AGENT); }
; #define XB_SPIN(cond, bar) do { unsigned _sp = 0; while (cond) { __builtin_amdgcn_s_sleep(1); \
;     if ((++_sp & 255u) == 0u) { if (xb_ld(&(bar)[XB_TMO])) break; if (_sp > XB_SPIN_CAP) { atomicAdd(&(bar)[XB_TMO], 1u); break; } } } } while (0)
; __device__ __forceinline__ void xcd_barrier(const int wv, const XcdBarrier& b) {
;     ...
;             XB_SPIN(xb_ld(&bar[XB_XGEN(b.x)]) == gen, bar);
.LBB0_538:
	s_and_b32 s16, s22, 0xff
	s_mov_b64 s[14:15], -1
	s_cmp_lg_u32 s16, 0
	s_mov_b64 s[16:17], -1
	s_sleep 1
	s_cbranch_scc1 .LBB0_542
	v_mov_b64_e32 v[4:5], s[2:3]
	global_load_dword v4, v[4:5], off offset:512 sc1
	s_mov_b64 s[16:17], 0
	s_mov_b64 s[18:19], -1
	s_waitcnt vmcnt(0) lgkmcnt(0)
	v_cmp_eq_u32_e32 vcc, 0, v4
	s_and_saveexec_b64 s[20:21], vcc
	s_cmp_lt_u32 s22, 0x400001
	s_cselect_b64 s[16:17], -1, 0
	s_xor_b64 s[18:19], exec, -1
	s_and_b64 s[16:17], s[16:17], exec
	s_or_b64 exec, exec, s[20:21]
.LBB0_542:
	s_andn2_b64 s[12:13], s[12:13], exec
	s_and_b64 s[18:19], s[18:19], exec
	s_or_b64 s[12:13], s[12:13], s[18:19]
	s_and_saveexec_b64 s[18:19], s[16:17]
	s_cbranch_execz .LBB0_537
	global_load_dword v4, v[2:3], off sc1
	s_add_i32 s22, s22, 1
	s_or_b64 s[12:13], s[12:13], exec
	s_waitcnt vmcnt(0) lgkmcnt(0)
	v_cmp_ne_u32_e32 vcc, v4, v1
	s_orn2_b64 s[14:15], vcc, exec
	s_branch .LBB0_537
.LBB0_544:
	s_or_b64 exec, exec, s[8:9]
	s_xor_b64 s[8:9], s[10:11], -1
	s_and_saveexec_b64 s[10:11], s[8:9]
	s_xor_b64 s[10:11], exec, s[10:11]
	s_cbranch_execz .LBB0_546
	v_mov_b64_e32 v[2:3], s[2:3]
	global_atomic_add v[2:3], v184, off offset:512

; __device__ __forceinline__ unsigned xb_ld(unsigned* p)              { return __hip_atomic_load(p, __ATOMIC_RELAXED, __HIP_MEMORY_SCOPE_AGENT); }
; __device__ __forceinline__ void xcd_barrier_complete(unsigned* bar, unsigned x, unsigned& nloc, unsigned& nx) {
;     ...
;     for (;;) {
;         sum = 0u; cnt = 0u; mine = 0u;
; #pragma unroll
;         for (unsigned j = 0; j < 16; ++j) { const unsigned c = xb_ld(&bar[XB_XCNT(j)]); sum += c; cnt += (c > 0u) ? 1u : 0u; mine = (j == x) ? c : mine; }
;         if (sum == G) break;
;         __builtin_amdgcn_s_sleep(1);
;         if ((++sp & 255u) == 0u) { if (xb_ld(&bar[XB_TMO])) break; if (sp > XB_SPIN_CAP) { atomicAdd(&bar[XB_TMO], 1u); break; } }
;     }
;     nloc = mine > 0u ? mine : 1u; nx = cnt > 0u ? cnt : 1u;
; }
.LBB0_607:
	global_load_dword v25, v[0:1], off offset:1024 sc1
	global_load_dword v10, v[0:1], off offset:1280 sc1
	global_load_dword v11, v[0:1], off offset:1536 sc1
	global_load_dword v12, v[0:1], off offset:1792 sc1
	global_load_dword v13, v[0:1], off offset:2048 sc1
	global_load_dword v14, v[0:1], off offset:2304 sc1
	global_load_dword v15, v[0:1], off offset:2560 sc1
	global_load_dword v16, v[0:1], off offset:2816 sc1
	global_load_dword v17, v[0:1], off offset:3072 sc1
	global_load_dword v18, v[0:1], off offset:3328 sc1
	global_load_dword v19, v[0:1], off offset:3584 sc1
	global_load_dword v20, v[0:1], off offset:3840 sc1
	global_load_dword v21, v[2:3], off sc1
	global_load_dword v22, v[4:5], off sc1
	global_load_dword v23, v[6:7], off sc1
	global_load_dword v24, v[8:9], off sc1
	s_or_b64 s[10:11], s[10:11], exec
	s_or_b64 s[8:9], s[8:9], exec
	s_waitcnt vmcnt(0) lgkmcnt(0)
	v_add_u32_e32 v26, v10, v25
	v_add_u32_e32 v26, v26, v11
	v_add_u32_e32 v26, v26, v12
	v_add_u32_e32 v26, v26, v13
	v_add_u32_e32 v26, v26, v14
	v_add_u32_e32 v26, v26, v15
	v_add_u32_e32 v26, v26, v16
	v_add_u32_e32 v26, v26, v17
	v_add_u32_e32 v26, v26, v18
	v_add_u32_e32 v26, v26, v19
	v_add_u32_e32 v26, v26, v20
	v_add_u32_e32 v26, v26, v21
	v_add_u32_e32 v26, v26, v22
	v_add_u32_e32 v26, v26, v23
	v_add_u32_e32 v26, v26, v24
	v_cmp_ne_u32_e32 vcc, s61, v26
	s_and_saveexec_b64 s[12:13], vcc
	s_cbranch_execz .LBB0_606
	s_and_b32 s16, s22, 0xff
	s_mov_b64 s[14:15], -1
	s_cmp_eq_u32 s16, 0
	s_mov_b64 s[18:19], -1
	s_mov_b64 s[16:17], -1
	s_sleep 1
	s_cbranch_scc1 .LBB0_610
	s_and_saveexec_b64 s[20:21], s[18:19]
	s_cbranch_execz .LBB0_605
	s_branch .LBB0_613
.LBB0_610:
	global_load_dword v26, v[0:1], off offset:512 sc1
	s_mov_b64 s[18:19], 0
	s_waitcnt vmcnt(0) lgkmcnt(0)
	v_cmp_eq_u32_e32 vcc, 0, v26
	s_and_saveexec_b64 s[20:21], vcc
	s_cmp_lt_u32 s22, 0x400001
	s_cselect_b64 s[18:19], -1, 0
	s_xor_b64 s[16:17], exec, -1
	s_and_b64 s[18:19], s[18:19], exec
	s_or_b64 exec, exec, s[20:21]
	s_and_saveexec_b64 s[20:21], s[18:19]
	s_cbranch_execz .LBB0_605

; __device__ __forceinline__ unsigned xb_ld(unsigned* p)              { return __hip_atomic_load(p, __ATOMIC_RELAXED, __HIP_MEMORY_SCOPE_AGENT); }
; __device__ __forceinline__ void xcd_barrier_complete(unsigned* bar, unsigned x, unsigned& nloc, unsigned& nx) {
;     ...
;         __builtin_amdgcn_s_sleep(1);
;         if ((++sp & 255u) == 0u) { if (xb_ld(&bar[XB_TMO])) break; if (sp > XB_SPIN_CAP) { atomicAdd(&bar[XB_TMO], 1u); break; } }
;     }
;     nloc = mine > 0u ? mine : 1u; nx = cnt > 0u ? cnt : 1u;
.LBB0_614:
	s_or_b64 exec, exec, s[4:5]
	s_xor_b64 s[4:5], s[6:7], -1
	s_and_saveexec_b64 s[6:7], s[4:5]
	s_xor_b64 s[4:5], exec, s[6:7]
	s_cbranch_execz .LBB0_616
	v_mov_b32_e32 v2, 1
	v_mov_b64_e32 v[0:1], s[2:3]
	global_atomic_add v[0:1], v2, off offset:512

; __device__ __forceinline__ unsigned xb_ld(unsigned* p)              { return __hip_atomic_load(p, __ATOMIC_RELAXED, __HIP_MEMORY_SCOPE_AGENT); }
; __device__ __forceinline__ unsigned xb_add(unsigned* p, unsigned v) { return __hip_atomic_fetch_add(p, v, __ATOMIC_RELAXED, __HIP_MEMORY_SCOPE_AGENT); }
; #define XB_SPIN(cond, bar) do { unsigned _sp = 0; while (cond) { __builtin_amdgcn_s_sleep(1); \
;     if ((++_sp & 255u) == 0u) { if (xb_ld(&(bar)[XB_TMO])) break; if (_sp > XB_SPIN_CAP) { atomicAdd(&(bar)[XB_TMO], 1u); break; } } } } while (0)
; __device__ __forceinline__ void xcd_barrier(const int wv, const XcdBarrier& b) {
;     ...
;         if (nloc == 0u) { xcd_barrier_complete(bar, b.x, nloc, nx); b.st[0] = nloc; b.st[1] = nx; }
;         const unsigned old = xb_add(&bar[XB_XSUB(b.x)], 1u);
;         const unsigned gen = old / nloc;
;         if (old + 1u == (gen + 1u) * nloc) {
;     ...
;             XB_SPIN(xb_ld(&bar[XB_XGEN(b.x)]) == gen, bar);
.LBB0_617:
	v_lshl_add_u64 v[0:1], v[178:179], 2, s[2:3]
	v_add_co_u32_e32 v6, vcc, 0x1000, v0
	v_mov_b32_e32 v3, 1
	s_nop 0
	v_addc_co_u32_e32 v7, vcc, 0, v1, vcc
	global_atomic_add v3, v[6:7], v3, off offset:1024 sc0
	v_cvt_f32_u32_e32 v5, v4
	v_sub_u32_e32 v6, 0, v4
	v_rcp_iflag_f32_e32 v5, v5
	s_nop 0
	v_mul_f32_e32 v5, 0x4f7ffffe, v5
	v_cvt_u32_f32_e32 v5, v5
	v_mul_lo_u32 v6, v6, v5
	v_mul_hi_u32 v6, v5, v6
	v_add_u32_e32 v5, v5, v6
	s_waitcnt vmcnt(0) lgkmcnt(0)
	v_mul_hi_u32 v5, v3, v5
	v_mul_lo_u32 v7, v5, v4
	v_add_u32_e32 v6, 1, v3
	v_sub_u32_e32 v3, v3, v7
	v_add_u32_e32 v8, 1, v5
	v_cmp_ge_u32_e32 vcc, v3, v4
	v_sub_u32_e32 v7, v3, v4
	s_nop 0
	v_cndmask_b32_e32 v5, v5, v8, vcc
	v_cndmask_b32_e32 v3, v3, v7, vcc
	v_add_u32_e32 v7, 1, v5
	v_cmp_ge_u32_e32 vcc, v3, v4
	s_nop 1
	v_cndmask_b32_e32 v3, v5, v7, vcc
	v_mad_u64_u32 v[4:5], s[4:5], v4, v3, v[4:5]
	v_cmp_ne_u32_e32 vcc, v6, v4
	s_and_saveexec_b64 s[4:5], vcc
	s_xor_b64 s[4:5], exec, s[4:5]
	s_cbranch_execz .LBB0_630
	v_add_co_u32_e32 v4, vcc, 0x2000, v0
	s_nop 1
	v_addc_co_u32_e32 v5, vcc, 0, v1, vcc
	global_load_dword v2, v[4:5], off offset:1024 sc1
	s_waitcnt vmcnt(0) lgkmcnt(0)
	v_cmp_eq_u32_e32 vcc, v2, v3
	s_and_saveexec_b64 s[6:7], vcc
	s_cbranch_execz .LBB0_629
	s_mov_b64 s[8:9], 0x2400
	v_lshl_add_u64 v[0:1], v[0:1], 0, s[8:9]
	s_mov_b32 s22, 1
	s_mov_b64 s[8:9], 0
	s_branch .LBB0_621

; __device__ __forceinline__ unsigned xb_ld(unsigned* p)              { return __hip_atomic_load(p, __ATOMIC_RELAXED, __HIP_MEMORY_SCOPE_AGENT); }
; #define XB_SPIN(cond, bar) do { unsigned _sp = 0; while (cond) { __builtin_amdgcn_s_sleep(1); \
;     if ((++_sp & 255u) == 0u) { if (xb_ld(&(bar)[XB_TMO])) break; if (_sp > XB_SPIN_CAP) { atomicAdd(&(bar)[XB_TMO], 1u); break; } } } } while (0)
; __device__ __forceinline__ void xcd_barrier(const int wv, const XcdBarrier& b) {
;     ...
;             XB_SPIN(xb_ld(&bar[XB_XGEN(b.x)]) == gen, bar);
.LBB0_621:
	s_and_b32 s16, s22, 0xff
	s_mov_b64 s[14:15], -1
	s_cmp_lg_u32 s16, 0
	s_mov_b64 s[16:17], -1
	s_sleep 1
	s_cbranch_scc1 .LBB0_625
	v_mov_b64_e32 v[4:5], s[2:3]
	global_load_dword v2, v[4:5], off offset:512 sc1
	s_mov_b64 s[16:17], 0
	s_mov_b64 s[18:19], -1
	s_waitcnt vmcnt(0) lgkmcnt(0)
	v_cmp_eq_u32_e32 vcc, 0, v2
	s_and_saveexec_b64 s[20:21], vcc
	s_cmp_lt_u32 s22, 0x400001
	s_cselect_b64 s[16:17], -1, 0
	s_xor_b64 s[18:19], exec, -1
	s_and_b64 s[16:17], s[16:17], exec
	s_or_b64 exec, exec, s[20:21]
.LBB0_625:
	s_andn2_b64 s[12:13], s[12:13], exec
	s_and_b64 s[18:19], s[18:19], exec
	s_or_b64 s[12:13], s[12:13], s[18:19]
	s_and_saveexec_b64 s[18:19], s[16:17]
	s_cbranch_execz .LBB0_620
	global_load_dword v2, v[0:1], off sc1
	s_add_i32 s22, s22, 1
	s_or_b64 s[12:13], s[12:13], exec
	s_waitcnt vmcnt(0) lgkmcnt(0)
	v_cmp_ne_u32_e32 vcc, v2, v3
	s_orn2_b64 s[14:15], vcc, exec
	s_branch .LBB0_620
.LBB0_627:
	s_or_b64 exec, exec, s[8:9]
	s_xor_b64 s[8:9], s[10:11], -1
	s_and_saveexec_b64 s[10:11], s[8:9]
	s_xor_b64 s[10:11], exec, s[10:11]
	s_cbranch_execz .LBB0_629
	v_mov_b32_e32 v2, 1
	v_mov_b64_e32 v[0:1], s[2:3]
	global_atomic_add v[0:1], v2, off offset:512

; __device__ __forceinline__ unsigned xb_ld(unsigned* p)              { return __hip_atomic_load(p, __ATOMIC_RELAXED, __HIP_MEMORY_SCOPE_AGENT); }
; __device__ __forceinline__ unsigned xb_add(unsigned* p, unsigned v) { return __hip_atomic_fetch_add(p, v, __ATOMIC_RELAXED, __HIP_MEMORY_SCOPE_AGENT); }
; #define XB_SPIN(cond, bar) do { unsigned _sp = 0; while (cond) { __builtin_amdgcn_s_sleep(1); \
;     if ((++_sp & 255u) == 0u) { if (xb_ld(&(bar)[XB_TMO])) break; if (_sp > XB_SPIN_CAP) { atomicAdd(&(bar)[XB_TMO], 1u); break; } } } } while (0)
; __device__ __forceinline__ void xcd_barrier(const int wv, const XcdBarrier& b) {
;     ...
;         if (old + 1u == (gen + 1u) * nloc) {
;             __builtin_amdgcn_fence(__ATOMIC_RELEASE, "agent");
;             asm volatile("s_waitcnt vmcnt(0)" ::: "memory");
;             const unsigned og = xb_add(&bar[XB_TOP], 1u);
;             const unsigned tg = og / nx;
;             if (og + 1u == (tg + 1u) * nx) xb_add(&bar[XB_TOPGEN], 1u);
;             else XB_SPIN(xb_ld(&bar[XB_TOPGEN]) == tg, bar);
.LBB0_630:
	s_andn2_saveexec_b64 s[4:5], s[4:5]
	s_cbranch_execz .LBB0_646
	v_mov_b32_e32 v3, s2
	v_add_co_u32_e32 v4, vcc, 0x3000, v3
	v_mov_b32_e32 v3, s3
	buffer_wbl2 sc1
	s_waitcnt vmcnt(0)
	v_addc_co_u32_e32 v5, vcc, 0, v3, vcc
	v_mov_b32_e32 v3, 1
	global_atomic_add v3, v[4:5], v3, off offset:1024 sc0
	v_cvt_f32_u32_e32 v4, v2
	v_sub_u32_e32 v5, 0, v2
	s_add_u32 s4, s2, 0x3500
	s_addc_u32 s5, s3, 0
	v_rcp_iflag_f32_e32 v4, v4
	s_mov_b64 s[8:9], -1
	v_mul_f32_e32 v4, 0x4f7ffffe, v4
	v_cvt_u32_f32_e32 v4, v4
	v_mul_lo_u32 v5, v5, v4
	v_mul_hi_u32 v5, v4, v5
	v_add_u32_e32 v4, v4, v5
	s_waitcnt vmcnt(0) lgkmcnt(0)
	v_mul_hi_u32 v4, v3, v4
	v_mul_lo_u32 v6, v4, v2
	v_add_u32_e32 v5, 1, v3
	v_sub_u32_e32 v3, v3, v6
	v_add_u32_e32 v7, 1, v4
	v_cmp_ge_u32_e32 vcc, v3, v2
	v_sub_u32_e32 v6, v3, v2
	s_nop 0
	v_cndmask_b32_e32 v4, v4, v7, vcc
	v_cndmask_b32_e32 v3, v3, v6, vcc
	v_add_u32_e32 v6, 1, v4
	v_cmp_ge_u32_e32 vcc, v3, v2
	s_nop 1
	v_cndmask_b32_e32 v4, v4, v6, vcc
	v_mad_u64_u32 v[2:3], s[6:7], v2, v4, v[2:3]
	v_cmp_ne_u32_e32 vcc, v5, v2
	v_mov_b64_e32 v[2:3], s[4:5]
	s_and_saveexec_b64 s[6:7], vcc
	s_cbranch_execz .LBB0_643
	v_mov_b64_e32 v[2:3], s[4:5]
	global_load_dword v2, v[2:3], off sc1
	s_mov_b64 s[12:13], 0
	s_waitcnt vmcnt(0) lgkmcnt(0)
	v_cmp_eq_u32_e32 vcc, v2, v4
	s_and_saveexec_b64 s[10:11], vcc
	s_cbranch_execz .LBB0_642
	s_add_u32 s8, s2, 0x200
	s_addc_u32 s9, s3, 0
	s_mov_b32 s22, 1
	s_mov_b64 s[2:3], 0
	s_branch .LBB0_635

; __device__ __forceinline__ unsigned xb_ld(unsigned* p)              { return __hip_atomic_load(p, __ATOMIC_RELAXED, __HIP_MEMORY_SCOPE_AGENT); }
; #define XB_SPIN(cond, bar) do { unsigned _sp = 0; while (cond) { __builtin_amdgcn_s_sleep(1); \
;     if ((++_sp & 255u) == 0u) { if (xb_ld(&(bar)[XB_TMO])) break; if (_sp > XB_SPIN_CAP) { atomicAdd(&(bar)[XB_TMO], 1u); break; } } } } while (0)
; __device__ __forceinline__ void xcd_barrier(const int wv, const XcdBarrier& b) {
;     ...
;             else XB_SPIN(xb_ld(&bar[XB_TOPGEN]) == tg, bar);
.LBB0_637:
	v_mov_b64_e32 v[2:3], s[8:9]
	global_load_dword v2, v[2:3], off sc1
	s_mov_b64 s[16:17], 0
	s_mov_b64 s[14:15], -1
	s_waitcnt vmcnt(0) lgkmcnt(0)
	v_cmp_eq_u32_e32 vcc, 0, v2
	s_and_saveexec_b64 s[18:19], vcc
	s_cmp_lt_u32 s22, 0x400001
	s_cselect_b64 s[16:17], -1, 0
	s_xor_b64 s[14:15], exec, -1
	s_and_b64 s[16:17], s[16:17], exec
	s_or_b64 exec, exec, s[18:19]
	s_mov_b64 s[18:19], -1
	s_and_saveexec_b64 s[20:21], s[16:17]
	s_cbranch_execz .LBB0_634
.LBB0_640:
	v_mov_b64_e32 v[2:3], s[4:5]
	global_load_dword v2, v[2:3], off sc1
	s_add_i32 s22, s22, 1
	s_or_b64 s[14:15], s[14:15], exec
	s_waitcnt vmcnt(0) lgkmcnt(0)
	v_cmp_ne_u32_e32 vcc, v2, v4
	s_orn2_b64 s[18:19], vcc, exec
	s_branch .LBB0_634

; __device__ __forceinline__ unsigned xb_ld(unsigned* p)              { return __hip_atomic_load(p, __ATOMIC_RELAXED, __HIP_MEMORY_SCOPE_AGENT); }
; __device__ __forceinline__ unsigned xb_add(unsigned* p, unsigned v) { return __hip_atomic_fetch_add(p, v, __ATOMIC_RELAXED, __HIP_MEMORY_SCOPE_AGENT); }
; #define XB_SPIN(cond, bar) do { unsigned _sp = 0; while (cond) { __builtin_amdgcn_s_sleep(1); \
;     if ((++_sp & 255u) == 0u) { if (xb_ld(&(bar)[XB_TMO])) break; if (_sp > XB_SPIN_CAP) { atomicAdd(&(bar)[XB_TMO], 1u); break; } } } } while (0)
; __device__ __forceinline__ void xcd_barrier(const int wv, const XcdBarrier& b) {
;     ...
;             if (og + 1u == (tg + 1u) * nx) xb_add(&bar[XB_TOPGEN], 1u);
;             else XB_SPIN(xb_ld(&bar[XB_TOPGEN]) == tg, bar);
;             __builtin_amdgcn_fence(__ATOMIC_ACQUIRE, "agent");
;             xb_add(&bar[XB_XGEN(b.x)], 1u);
;             asm volatile("s_waitcnt vmcnt(0)" ::: "memory");
.LBB0_643:
	s_or_b64 exec, exec, s[6:7]
	s_and_saveexec_b64 s[2:3], s[8:9]
	s_cbranch_execz .LBB0_645
	v_mov_b32_e32 v4, 1
	global_atomic_add v[2:3], v4, off
.LBB0_645:
	s_or_b64 exec, exec, s[2:3]
	v_add_co_u32_e32 v0, vcc, 0x2000, v0
	v_mov_b32_e32 v2, 1
	s_nop 0
	v_addc_co_u32_e32 v1, vcc, 0, v1, vcc
	s_waitcnt vmcnt(0) lgkmcnt(0)
	buffer_inv sc1
	global_atomic_add v[0:1], v2, off offset:1024
	s_waitcnt vmcnt(0)

; __device__ __forceinline__ unsigned xb_ld(unsigned* p)              { return __hip_atomic_load(p, __ATOMIC_RELAXED, __HIP_MEMORY_SCOPE_AGENT); }
; __device__ __forceinline__ void xcd_barrier_complete(unsigned* bar, unsigned x, unsigned& nloc, unsigned& nx) {
;     ...
;     for (;;) {
;         sum = 0u; cnt = 0u; mine = 0u;
; #pragma unroll
;         for (unsigned j = 0; j < 16; ++j) { const unsigned c = xb_ld(&bar[XB_XCNT(j)]); sum += c; cnt += (c > 0u) ? 1u : 0u; mine = (j == x) ? c : mine; }
;         if (sum == G) break;
;         __builtin_amdgcn_s_sleep(1);
;         if ((++sp & 255u) == 0u) { if (xb_ld(&bar[XB_TMO])) break; if (sp > XB_SPIN_CAP) { atomicAdd(&bar[XB_TMO], 1u); break; } }
;     }
;     nloc = mine > 0u ? mine : 1u; nx = cnt > 0u ? cnt : 1u;
; }
.LBB0_735:
	global_load_dword v25, v[0:1], off offset:1024 sc1
	global_load_dword v10, v[0:1], off offset:1280 sc1
	global_load_dword v11, v[0:1], off offset:1536 sc1
	global_load_dword v12, v[0:1], off offset:1792 sc1
	global_load_dword v13, v[0:1], off offset:2048 sc1
	global_load_dword v14, v[0:1], off offset:2304 sc1
	global_load_dword v15, v[0:1], off offset:2560 sc1
	global_load_dword v16, v[0:1], off offset:2816 sc1
	global_load_dword v17, v[0:1], off offset:3072 sc1
	global_load_dword v18, v[0:1], off offset:3328 sc1
	global_load_dword v19, v[0:1], off offset:3584 sc1
	global_load_dword v20, v[0:1], off offset:3840 sc1
	global_load_dword v21, v[2:3], off sc1
	global_load_dword v22, v[4:5], off sc1
	global_load_dword v23, v[6:7], off sc1
	global_load_dword v24, v[8:9], off sc1
	s_or_b64 s[8:9], s[8:9], exec
	s_or_b64 s[6:7], s[6:7], exec
	s_waitcnt vmcnt(0) lgkmcnt(0)
	v_add_u32_e32 v26, v10, v25
	v_add_u32_e32 v26, v26, v11
	v_add_u32_e32 v26, v26, v12
	v_add_u32_e32 v26, v26, v13
	v_add_u32_e32 v26, v26, v14
	v_add_u32_e32 v26, v26, v15
	v_add_u32_e32 v26, v26, v16
	v_add_u32_e32 v26, v26, v17
	v_add_u32_e32 v26, v26, v18
	v_add_u32_e32 v26, v26, v19
	v_add_u32_e32 v26, v26, v20
	v_add_u32_e32 v26, v26, v21
	v_add_u32_e32 v26, v26, v22
	v_add_u32_e32 v26, v26, v23
	v_add_u32_e32 v26, v26, v24
	v_cmp_ne_u32_e32 vcc, s61, v26
	s_and_saveexec_b64 s[10:11], vcc
	s_cbranch_execz .LBB0_734
	s_and_b32 s14, s20, 0xff
	s_mov_b64 s[12:13], -1
	s_cmp_eq_u32 s14, 0
	s_mov_b64 s[16:17], -1
	s_mov_b64 s[14:15], -1
	s_sleep 1
	s_cbranch_scc1 .LBB0_738
	s_and_saveexec_b64 s[18:19], s[16:17]
	s_cbranch_execz .LBB0_733
	s_branch .LBB0_741
.LBB0_738:
	global_load_dword v26, v[0:1], off offset:512 sc1
	s_mov_b64 s[16:17], 0
	s_waitcnt vmcnt(0) lgkmcnt(0)
	v_cmp_eq_u32_e32 vcc, 0, v26
	s_and_saveexec_b64 s[18:19], vcc
	s_cmp_lt_u32 s20, 0x400001
	s_cselect_b64 s[16:17], -1, 0
	s_xor_b64 s[14:15], exec, -1
	s_and_b64 s[16:17], s[16:17], exec
	s_or_b64 exec, exec, s[18:19]
	s_and_saveexec_b64 s[18:19], s[16:17]
	s_cbranch_execz .LBB0_733

; __device__ __forceinline__ unsigned xb_ld(unsigned* p)              { return __hip_atomic_load(p, __ATOMIC_RELAXED, __HIP_MEMORY_SCOPE_AGENT); }
; __device__ __forceinline__ void xcd_barrier_complete(unsigned* bar, unsigned x, unsigned& nloc, unsigned& nx) {
;     ...
;         __builtin_amdgcn_s_sleep(1);
;         if ((++sp & 255u) == 0u) { if (xb_ld(&bar[XB_TMO])) break; if (sp > XB_SPIN_CAP) { atomicAdd(&bar[XB_TMO], 1u); break; } }
;     }
;     nloc = mine > 0u ? mine : 1u; nx = cnt > 0u ? cnt : 1u;
.LBB0_742:
	s_or_b64 exec, exec, s[2:3]
	s_xor_b64 s[2:3], s[4:5], -1
	s_and_saveexec_b64 s[4:5], s[2:3]
	s_xor_b64 s[2:3], exec, s[4:5]
	s_cbranch_execz .LBB0_744
	v_mov_b32_e32 v2, 1
	v_mov_b64_e32 v[0:1], s[58:59]
	global_atomic_add v[0:1], v2, off offset:512

; __device__ __forceinline__ unsigned xb_ld(unsigned* p)              { return __hip_atomic_load(p, __ATOMIC_RELAXED, __HIP_MEMORY_SCOPE_AGENT); }
; __device__ __forceinline__ unsigned xb_add(unsigned* p, unsigned v) { return __hip_atomic_fetch_add(p, v, __ATOMIC_RELAXED, __HIP_MEMORY_SCOPE_AGENT); }
; #define XB_SPIN(cond, bar) do { unsigned _sp = 0; while (cond) { __builtin_amdgcn_s_sleep(1); \
;     if ((++_sp & 255u) == 0u) { if (xb_ld(&(bar)[XB_TMO])) break; if (_sp > XB_SPIN_CAP) { atomicAdd(&(bar)[XB_TMO], 1u); break; } } } } while (0)
; __device__ __forceinline__ void xcd_barrier(const int wv, const XcdBarrier& b) {
;     ...
;         if (nloc == 0u) { xcd_barrier_complete(bar, b.x, nloc, nx); b.st[0] = nloc; b.st[1] = nx; }
;         const unsigned old = xb_add(&bar[XB_XSUB(b.x)], 1u);
;         const unsigned gen = old / nloc;
;         if (old + 1u == (gen + 1u) * nloc) {
;     ...
;             XB_SPIN(xb_ld(&bar[XB_XGEN(b.x)]) == gen, bar);
.LBB0_745:
	v_lshl_add_u64 v[0:1], v[178:179], 2, s[58:59]
	v_add_co_u32_e32 v6, vcc, 0x1000, v0
	v_mov_b32_e32 v3, 1
	s_nop 0
	v_addc_co_u32_e32 v7, vcc, 0, v1, vcc
	global_atomic_add v3, v[6:7], v3, off offset:1024 sc0
	v_cvt_f32_u32_e32 v5, v4
	v_sub_u32_e32 v6, 0, v4
	v_rcp_iflag_f32_e32 v5, v5
	s_nop 0
	v_mul_f32_e32 v5, 0x4f7ffffe, v5
	v_cvt_u32_f32_e32 v5, v5
	v_mul_lo_u32 v6, v6, v5
	v_mul_hi_u32 v6, v5, v6
	v_add_u32_e32 v5, v5, v6
	s_waitcnt vmcnt(0) lgkmcnt(0)
	v_mul_hi_u32 v5, v3, v5
	v_mul_lo_u32 v7, v5, v4
	v_add_u32_e32 v6, 1, v3
	v_sub_u32_e32 v3, v3, v7
	v_add_u32_e32 v8, 1, v5
	v_cmp_ge_u32_e32 vcc, v3, v4
	v_sub_u32_e32 v7, v3, v4
	s_nop 0
	v_cndmask_b32_e32 v5, v5, v8, vcc
	v_cndmask_b32_e32 v3, v3, v7, vcc
	v_add_u32_e32 v7, 1, v5
	v_cmp_ge_u32_e32 vcc, v3, v4
	s_nop 1
	v_cndmask_b32_e32 v3, v5, v7, vcc
	v_mad_u64_u32 v[4:5], s[2:3], v4, v3, v[4:5]
	v_cmp_ne_u32_e32 vcc, v6, v4
	s_and_saveexec_b64 s[2:3], vcc
	s_xor_b64 s[2:3], exec, s[2:3]
	s_cbranch_execz .LBB0_758
	v_add_co_u32_e32 v4, vcc, 0x2000, v0
	s_nop 1
	v_addc_co_u32_e32 v5, vcc, 0, v1, vcc
	global_load_dword v2, v[4:5], off offset:1024 sc1
	s_waitcnt vmcnt(0) lgkmcnt(0)
	v_cmp_eq_u32_e32 vcc, v2, v3
	s_and_saveexec_b64 s[4:5], vcc
	s_cbranch_execz .LBB0_757
	s_mov_b64 s[6:7], 0x2400
	v_lshl_add_u64 v[0:1], v[0:1], 0, s[6:7]
	s_mov_b32 s20, 1
	s_mov_b64 s[6:7], 0
	s_branch .LBB0_749

; __device__ __forceinline__ unsigned xb_ld(unsigned* p)              { return __hip_atomic_load(p, __ATOMIC_RELAXED, __HIP_MEMORY_SCOPE_AGENT); }
; #define XB_SPIN(cond, bar) do { unsigned _sp = 0; while (cond) { __builtin_amdgcn_s_sleep(1); \
;     if ((++_sp & 255u) == 0u) { if (xb_ld(&(bar)[XB_TMO])) break; if (_sp > XB_SPIN_CAP) { atomicAdd(&(bar)[XB_TMO], 1u); break; } } } } while (0)
; __device__ __forceinline__ void xcd_barrier(const int wv, const XcdBarrier& b) {
;     ...
;             XB_SPIN(xb_ld(&bar[XB_XGEN(b.x)]) == gen, bar);
.LBB0_749:
	s_and_b32 s14, s20, 0xff
	s_mov_b64 s[12:13], -1
	s_cmp_lg_u32 s14, 0
	s_mov_b64 s[14:15], -1
	s_sleep 1
	s_cbranch_scc1 .LBB0_753
	v_mov_b64_e32 v[4:5], s[58:59]
	global_load_dword v2, v[4:5], off offset:512 sc1
	s_mov_b64 s[14:15], 0
	s_mov_b64 s[16:17], -1
	s_waitcnt vmcnt(0) lgkmcnt(0)
	v_cmp_eq_u32_e32 vcc, 0, v2
	s_and_saveexec_b64 s[18:19], vcc
	s_cmp_lt_u32 s20, 0x400001
	s_cselect_b64 s[14:15], -1, 0
	s_xor_b64 s[16:17], exec, -1
	s_and_b64 s[14:15], s[14:15], exec
	s_or_b64 exec, exec, s[18:19]
.LBB0_753:
	s_andn2_b64 s[10:11], s[10:11], exec
	s_and_b64 s[16:17], s[16:17], exec
	s_or_b64 s[10:11], s[10:11], s[16:17]
	s_and_saveexec_b64 s[16:17], s[14:15]
	s_cbranch_execz .LBB0_748
	global_load_dword v2, v[0:1], off sc1
	s_add_i32 s20, s20, 1
	s_or_b64 s[10:11], s[10:11], exec
	s_waitcnt vmcnt(0) lgkmcnt(0)
	v_cmp_ne_u32_e32 vcc, v2, v3
	s_orn2_b64 s[12:13], vcc, exec
	s_branch .LBB0_748
.LBB0_755:
	s_or_b64 exec, exec, s[6:7]
	s_xor_b64 s[6:7], s[8:9], -1
	s_and_saveexec_b64 s[8:9], s[6:7]
	s_xor_b64 s[8:9], exec, s[8:9]
	s_cbranch_execz .LBB0_757
	v_mov_b32_e32 v2, 1
	v_mov_b64_e32 v[0:1], s[58:59]
	global_atomic_add v[0:1], v2, off offset:512

; __device__ __forceinline__ unsigned xb_ld(unsigned* p)              { return __hip_atomic_load(p, __ATOMIC_RELAXED, __HIP_MEMORY_SCOPE_AGENT); }
; __device__ __forceinline__ unsigned xb_add(unsigned* p, unsigned v) { return __hip_atomic_fetch_add(p, v, __ATOMIC_RELAXED, __HIP_MEMORY_SCOPE_AGENT); }
; #define XB_SPIN(cond, bar) do { unsigned _sp = 0; while (cond) { __builtin_amdgcn_s_sleep(1); \
;     if ((++_sp & 255u) == 0u) { if (xb_ld(&(bar)[XB_TMO])) break; if (_sp > XB_SPIN_CAP) { atomicAdd(&(bar)[XB_TMO], 1u); break; } } } } while (0)
; __device__ __forceinline__ void xcd_barrier(const int wv, const XcdBarrier& b) {
;     ...
;         if (old + 1u == (gen + 1u) * nloc) {
;             __builtin_amdgcn_fence(__ATOMIC_RELEASE, "agent");
;             asm volatile("s_waitcnt vmcnt(0)" ::: "memory");
;             const unsigned og = xb_add(&bar[XB_TOP], 1u);
;             const unsigned tg = og / nx;
;             if (og + 1u == (tg + 1u) * nx) xb_add(&bar[XB_TOPGEN], 1u);
;             else XB_SPIN(xb_ld(&bar[XB_TOPGEN]) == tg, bar);
.LBB0_758:
	s_andn2_saveexec_b64 s[2:3], s[2:3]
	s_cbranch_execz .LBB0_774
	v_mov_b32_e32 v3, s58
	v_add_co_u32_e32 v4, vcc, 0x3000, v3
	v_mov_b32_e32 v3, s59
	buffer_wbl2 sc1
	s_waitcnt vmcnt(0)
	v_addc_co_u32_e32 v5, vcc, 0, v3, vcc
	v_mov_b32_e32 v3, 1
	global_atomic_add v3, v[4:5], v3, off offset:1024 sc0
	v_cvt_f32_u32_e32 v4, v2
	v_sub_u32_e32 v5, 0, v2
	s_add_u32 s2, s58, 0x3500
	s_addc_u32 s3, s59, 0
	v_rcp_iflag_f32_e32 v4, v4
	s_mov_b64 s[6:7], -1
	v_mul_f32_e32 v4, 0x4f7ffffe, v4
	v_cvt_u32_f32_e32 v4, v4
	v_mul_lo_u32 v5, v5, v4
	v_mul_hi_u32 v5, v4, v5
	v_add_u32_e32 v4, v4, v5
	s_waitcnt vmcnt(0) lgkmcnt(0)
	v_mul_hi_u32 v4, v3, v4
	v_mul_lo_u32 v6, v4, v2
	v_add_u32_e32 v5, 1, v3
	v_sub_u32_e32 v3, v3, v6
	v_add_u32_e32 v7, 1, v4
	v_cmp_ge_u32_e32 vcc, v3, v2
	v_sub_u32_e32 v6, v3, v2
	s_nop 0
	v_cndmask_b32_e32 v4, v4, v7, vcc
	v_cndmask_b32_e32 v3, v3, v6, vcc
	v_add_u32_e32 v6, 1, v4
	v_cmp_ge_u32_e32 vcc, v3, v2
	s_nop 1
	v_cndmask_b32_e32 v4, v4, v6, vcc
	v_mad_u64_u32 v[2:3], s[4:5], v2, v4, v[2:3]
	v_cmp_ne_u32_e32 vcc, v5, v2
	v_mov_b64_e32 v[2:3], s[2:3]
	s_and_saveexec_b64 s[4:5], vcc
	s_cbranch_execz .LBB0_771
	v_mov_b64_e32 v[2:3], s[2:3]
	global_load_dword v2, v[2:3], off sc1
	s_mov_b64 s[10:11], 0
	s_waitcnt vmcnt(0) lgkmcnt(0)
	v_cmp_eq_u32_e32 vcc, v2, v4
	s_and_saveexec_b64 s[8:9], vcc
	s_cbranch_execz .LBB0_770
	s_add_u32 s6, s58, 0x200
	s_addc_u32 s7, s59, 0
	s_mov_b32 s22, 1
	s_branch .LBB0_763

; __device__ __forceinline__ unsigned xb_ld(unsigned* p)              { return __hip_atomic_load(p, __ATOMIC_RELAXED, __HIP_MEMORY_SCOPE_AGENT); }
; #define XB_SPIN(cond, bar) do { unsigned _sp = 0; while (cond) { __builtin_amdgcn_s_sleep(1); \
;     if ((++_sp & 255u) == 0u) { if (xb_ld(&(bar)[XB_TMO])) break; if (_sp > XB_SPIN_CAP) { atomicAdd(&(bar)[XB_TMO], 1u); break; } } } } while (0)
; __device__ __forceinline__ void xcd_barrier(const int wv, const XcdBarrier& b) {
;     ...
;             else XB_SPIN(xb_ld(&bar[XB_TOPGEN]) == tg, bar);
.LBB0_765:
	v_mov_b64_e32 v[2:3], s[6:7]
	global_load_dword v2, v[2:3], off sc1
	s_mov_b64 s[16:17], 0
	s_mov_b64 s[14:15], -1
	s_waitcnt vmcnt(0) lgkmcnt(0)
	v_cmp_eq_u32_e32 vcc, 0, v2
	s_and_saveexec_b64 s[18:19], vcc
	s_cmp_lt_u32 s22, 0x400001
	s_cselect_b64 s[16:17], -1, 0
	s_xor_b64 s[14:15], exec, -1
	s_and_b64 s[16:17], s[16:17], exec
	s_or_b64 exec, exec, s[18:19]
	s_mov_b64 s[18:19], -1
	s_and_saveexec_b64 s[20:21], s[16:17]
	s_cbranch_execz .LBB0_762
.LBB0_768:
	v_mov_b64_e32 v[2:3], s[2:3]
	global_load_dword v2, v[2:3], off sc1
	s_add_i32 s22, s22, 1
	s_or_b64 s[14:15], s[14:15], exec
	s_waitcnt vmcnt(0) lgkmcnt(0)
	v_cmp_ne_u32_e32 vcc, v2, v4
	s_orn2_b64 s[18:19], vcc, exec
	s_branch .LBB0_762

; __device__ __forceinline__ unsigned xb_ld(unsigned* p)              { return __hip_atomic_load(p, __ATOMIC_RELAXED, __HIP_MEMORY_SCOPE_AGENT); }
; __device__ __forceinline__ unsigned xb_add(unsigned* p, unsigned v) { return __hip_atomic_fetch_add(p, v, __ATOMIC_RELAXED, __HIP_MEMORY_SCOPE_AGENT); }
; #define XB_SPIN(cond, bar) do { unsigned _sp = 0; while (cond) { __builtin_amdgcn_s_sleep(1); \
;     if ((++_sp & 255u) == 0u) { if (xb_ld(&(bar)[XB_TMO])) break; if (_sp > XB_SPIN_CAP) { atomicAdd(&(bar)[XB_TMO], 1u); break; } } } } while (0)
; __device__ __forceinline__ void xcd_barrier(const int wv, const XcdBarrier& b) {
;     ...
;             if (og + 1u == (tg + 1u) * nx) xb_add(&bar[XB_TOPGEN], 1u);
;             else XB_SPIN(xb_ld(&bar[XB_TOPGEN]) == tg, bar);
;             __builtin_amdgcn_fence(__ATOMIC_ACQUIRE, "agent");
;             xb_add(&bar[XB_XGEN(b.x)], 1u);
.LBB0_771:
	s_or_b64 exec, exec, s[4:5]
	s_and_saveexec_b64 s[2:3], s[6:7]
	s_cbranch_execz .LBB0_773
	v_mov_b32_e32 v4, 1
	global_atomic_add v[2:3], v4, off
